# EpiRes epilogues of the w_out and w_o_mem GEMMs: 16 base loads per tile hoisted to the top of the epilogue
# speedup vs baseline: 1.0620x; 1.0009x over previous
; __device__ __forceinline__ unsigned cvt_pk_bf16(float lo, float hi) { unsigned r; asm volatile("v_cvt_pk_bf16_f32 %0, %1, %2" : "=v"(r) : "v"(lo), "v"(hi)); return r; }
;     __device__ __forceinline__ void operator()(const f32x4 (&acc)[2][2][4][2], const Unit& u, int wr, int wc, int fr, int fq) const {
;         const int row0 = u.pm * BM + wr * 64 + fr; const int col0 = u.pn * BM + wc * 32 + 8 * fq;
; #pragma unroll
;         for (int ai = 0; ai < 2; ++ai)
; #pragma unroll
;             for (int m = 0; m < 4; ++m) { const int row = row0 + ai * HALF + m * 16; const size_t off = (size_t)row * ldc + col0; float part = 0.f;
; #pragma unroll
;                 for (int bj = 0; bj < 2; ++bj) { const size_t idx = off + bj * HALF;
;                     f32x4 b0, b1;
;                     if constexpr (BASE_BF16) { const u32x4 r = *(const u32x4*)(baseb + idx);
;                         b0 = (f32x4){__builtin_bit_cast(float, r.x << 16), __builtin_bit_cast(float, r.x & 0xffff0000u), __builtin_bit_cast(float, r.y << 16), __builtin_bit_cast(float, r.y & 0xffff0000u)};
;                         b1 = (f32x4){__builtin_bit_cast(float, r.z << 16), __builtin_bit_cast(float, r.z & 0xffff0000u), __builtin_bit_cast(float, r.w << 16), __builtin_bit_cast(float, r.w & 0xffff0000u)}; }
;                     else { b0 = *(const f32x4*)(base + idx); b1 = *(const f32x4*)(base + idx + 4); }
;                     const f32x4 o0 = b0 + acc[ai][bj][m][0] * alpha, o1 = b1 + acc[ai][bj][m][1] * alpha;
;                     if constexpr (WRITE_F32) { *(f32x4*)(out + idx) = o0; *(f32x4*)(out + idx + 4) = o1; }
;                     if constexpr (WRITE_XB) {
;                         part += (o0[0] * o0[0] + o0[1] * o0[1]) + (o0[2] * o0[2] + o0[3] * o0[3]) + (o1[0] * o1[0] + o1[1] * o1[1]) + (o1[2] * o1[2] + o1[3] * o1[3]);
;                         u32x4 w; w.x = cvt_pk_bf16(o0[0], o0[1]); w.y = cvt_pk_bf16(o0[2], o0[3]); w.z = cvt_pk_bf16(o1[0], o1[1]); w.w = cvt_pk_bf16(o1[2], o1[3]);
;                         *(u32x4*)(xb + idx) = w; } }
;                 if constexpr (WRITE_XB) { part += __shfl_xor(part, 16); part += __shfl_xor(part, 32);
;                     if (fq == 0) atomicAdd(ss + row, part); } }
;     }
.LBB0_687:
	v_lshl_add_u32 v146, s42, 8, v148
	v_lshl_or_b32 v144, s44, 8, v150
	v_ashrrev_i32_e32 v147, 31, v146
	v_ashrrev_i32_e32 v145, 31, v144
	v_mov_b32_e32 v248, v146
	v_lshl_add_u32 v248, v248, 11, v144
	v_lshlrev_b32_e32 v248, 1, v248
	global_load_dwordx4 v[172:175], v248, s[14:15]
	global_load_dwordx4 v[176:179], v248, s[14:15] offset:256
	v_add_u32_e32 v249, 16, v146
	v_lshl_add_u32 v249, v249, 11, v144
	v_lshlrev_b32_e32 v249, 1, v249
	global_load_dwordx4 v[180:183], v249, s[14:15]
	global_load_dwordx4 v[184:187], v249, s[14:15] offset:256
	v_add_u32_e32 v250, 32, v146
	v_lshl_add_u32 v250, v250, 11, v144
	v_lshlrev_b32_e32 v250, 1, v250
	global_load_dwordx4 v[188:191], v250, s[14:15]
	global_load_dwordx4 v[192:195], v250, s[14:15] offset:256
	v_add_u32_e32 v251, 48, v146
	v_lshl_add_u32 v251, v251, 11, v144
	v_lshlrev_b32_e32 v251, 1, v251
	global_load_dwordx4 v[196:199], v251, s[14:15]
	global_load_dwordx4 v[200:203], v251, s[14:15] offset:256
	v_add_u32_e32 v252, 0x80, v146
	v_lshl_add_u32 v252, v252, 11, v144
	v_lshlrev_b32_e32 v252, 1, v252
	global_load_dwordx4 v[204:207], v252, s[14:15]
	global_load_dwordx4 v[208:211], v252, s[14:15] offset:256
	v_add_u32_e32 v253, 0x90, v146
	v_lshl_add_u32 v253, v253, 11, v144
	v_lshlrev_b32_e32 v253, 1, v253
	global_load_dwordx4 v[212:215], v253, s[14:15]
	global_load_dwordx4 v[220:223], v253, s[14:15] offset:256
	v_add_u32_e32 v254, 0xa0, v146
	v_lshl_add_u32 v254, v254, 11, v144
	v_lshlrev_b32_e32 v254, 1, v254
	global_load_dwordx4 v[224:227], v254, s[14:15]
	global_load_dwordx4 v[228:231], v254, s[14:15] offset:256
	v_add_u32_e32 v255, 0xb0, v146
	v_lshl_add_u32 v255, v255, 11, v144
	v_lshlrev_b32_e32 v255, 1, v255
	global_load_dwordx4 v[232:235], v255, s[14:15]
	global_load_dwordx4 v[236:239], v255, s[14:15] offset:256
	v_lshlrev_b64 v[156:157], 11, v[146:147]
	v_lshl_add_u64 v[156:157], v[156:157], 0, v[144:145]
	v_lshlrev_b64 v[160:161], 1, v[156:157]
	v_lshl_add_u64 v[156:157], s[14:15], 0, v[160:161]
	s_waitcnt vmcnt(15)
	v_mov_b32_e32 v156, v172
	v_mov_b32_e32 v157, v173
	v_mov_b32_e32 v158, v174
	v_mov_b32_e32 v159, v175
	v_lshl_add_u64 v[162:163], s[16:17], 0, v[160:161]
	v_or_b32_e32 v160, 0x100, v160
	v_lshl_add_u64 v[164:165], s[14:15], 0, v[160:161]
	v_xor_b32_e32 v155, 32, v154
	v_lshlrev_b32_e32 v166, 16, v156
	v_and_b32_e32 v167, 0xffff0000, v156
	v_lshlrev_b32_e32 v156, 16, v157
	v_and_b32_e32 v157, 0xffff0000, v157
	v_lshlrev_b32_e32 v168, 16, v158
	v_and_b32_e32 v169, 0xffff0000, v158
	v_lshlrev_b32_e32 v158, 16, v159
	v_and_b32_e32 v159, 0xffff0000, v159
	v_pk_add_f32 v[126:127], v[126:127], v[156:157]
	v_pk_add_f32 v[166:167], v[124:125], v[166:167]
	v_pk_add_f32 v[170:171], v[122:123], v[158:159]
	v_pk_add_f32 v[168:169], v[120:121], v[168:169]
	v_cvt_pk_bf16_f32 v122, v166, v167
	v_cvt_pk_bf16_f32 v123, v126, v127
	v_mul_f32_e32 v127, v127, v127
	v_cvt_pk_bf16_f32 v124, v168, v169
	v_cvt_pk_bf16_f32 v125, v170, v171
	s_waitcnt vmcnt(14)
	v_mov_b32_e32 v156, v176
	v_mov_b32_e32 v157, v177
	v_mov_b32_e32 v158, v178
	v_mov_b32_e32 v159, v179
	v_mul_f32_e32 v164, v167, v167
	v_mul_f32_e32 v165, v169, v169
	v_fmac_f32_e32 v164, v166, v166
	v_fmac_f32_e32 v127, v126, v126
	v_mul_f32_e32 v167, v171, v171
	v_fmac_f32_e32 v165, v168, v168
	v_add_f32_e32 v126, v164, v127
	v_fmac_f32_e32 v167, v170, v170
	v_add_f32_e32 v126, v165, v126
	v_add_f32_e32 v166, v167, v126
	v_and_b32_e32 v121, 64, v154
	v_xor_b32_e32 v120, 16, v154
	v_add_u32_e32 v121, 64, v121
	v_cmp_lt_i32_e32 vcc, v120, v121
	global_store_dwordx4 v[162:163], v[122:125], off
	v_lshlrev_b32_e32 v126, 16, v156
	v_and_b32_e32 v127, 0xffff0000, v156
	v_lshlrev_b32_e32 v156, 16, v157
	v_and_b32_e32 v157, 0xffff0000, v157
	v_lshlrev_b32_e32 v164, 16, v158
	v_and_b32_e32 v165, 0xffff0000, v158
	v_pk_add_f32 v[118:119], v[118:119], v[156:157]
	v_pk_add_f32 v[116:117], v[116:117], v[126:127]
	v_lshlrev_b32_e32 v158, 16, v159
	v_and_b32_e32 v159, 0xffff0000, v159
	v_pk_add_f32 v[156:157], v[112:113], v[164:165]
	v_mul_f32_e32 v112, v117, v117
	v_mul_f32_e32 v113, v119, v119
	v_pk_add_f32 v[126:127], v[114:115], v[158:159]
	v_mul_f32_e32 v114, v157, v157
	v_fmac_f32_e32 v112, v116, v116
	v_fmac_f32_e32 v113, v118, v118
	v_mul_f32_e32 v115, v127, v127
	v_fmac_f32_e32 v114, v156, v156
	v_add_f32_e32 v112, v112, v113
	v_fmac_f32_e32 v115, v126, v126
	v_add_f32_e32 v112, v114, v112
	v_cndmask_b32_e32 v120, v154, v120, vcc
	v_add_f32_e32 v112, v115, v112
	v_lshlrev_b32_e32 v120, 2, v120
	v_add_f32_e32 v112, v166, v112
	ds_bpermute_b32 v113, v120, v112
	v_cmp_lt_i32_e32 vcc, v155, v121
	v_lshl_add_u64 v[122:123], s[16:17], 0, v[160:161]
	v_cvt_pk_bf16_f32 v116, v116, v117
	v_cvt_pk_bf16_f32 v117, v118, v119
	s_waitcnt lgkmcnt(0)
	v_add_f32_e32 v112, v112, v113
	v_cndmask_b32_e32 v114, v154, v155, vcc
	v_lshlrev_b32_e32 v114, 2, v114
	ds_bpermute_b32 v113, v114, v112
	v_cvt_pk_bf16_f32 v118, v156, v157
	v_cvt_pk_bf16_f32 v119, v126, v127
	global_store_dwordx4 v[122:123], v[116:119], off
	s_and_saveexec_b64 s[42:43], s[2:3]
	s_cbranch_execz .LBB0_689
	v_lshl_add_u64 v[116:117], v[146:147], 2, s[18:19]
	s_waitcnt lgkmcnt(0)
	v_add_f32_e32 v112, v112, v113
	global_atomic_add_f32 v[116:117], v112, off
; __device__ __forceinline__ unsigned cvt_pk_bf16(float lo, float hi) { unsigned r; asm volatile("v_cvt_pk_bf16_f32 %0, %1, %2" : "=v"(r) : "v"(lo), "v"(hi)); return r; }
;     __device__ __forceinline__ void operator()(const f32x4 (&acc)[2][2][4][2], const Unit& u, int wr, int wc, int fr, int fq) const {
;         const int row0 = u.pm * BM + wr * 64 + fr; const int col0 = u.pn * BM + wc * 32 + 8 * fq;
; #pragma unroll
;         for (int ai = 0; ai < 2; ++ai)
; #pragma unroll
;             for (int m = 0; m < 4; ++m) { const int row = row0 + ai * HALF + m * 16; const size_t off = (size_t)row * ldc + col0; float part = 0.f;
; #pragma unroll
;                 for (int bj = 0; bj < 2; ++bj) { const size_t idx = off + bj * HALF;
;                     f32x4 b0, b1;
;                     if constexpr (BASE_BF16) { const u32x4 r = *(const u32x4*)(baseb + idx);
;                         b0 = (f32x4){__builtin_bit_cast(float, r.x << 16), __builtin_bit_cast(float, r.x & 0xffff0000u), __builtin_bit_cast(float, r.y << 16), __builtin_bit_cast(float, r.y & 0xffff0000u)};
;                         b1 = (f32x4){__builtin_bit_cast(float, r.z << 16), __builtin_bit_cast(float, r.z & 0xffff0000u), __builtin_bit_cast(float, r.w << 16), __builtin_bit_cast(float, r.w & 0xffff0000u)}; }
;                     else { b0 = *(const f32x4*)(base + idx); b1 = *(const f32x4*)(base + idx + 4); }
;                     const f32x4 o0 = b0 + acc[ai][bj][m][0] * alpha, o1 = b1 + acc[ai][bj][m][1] * alpha;
;                     if constexpr (WRITE_F32) { *(f32x4*)(out + idx) = o0; *(f32x4*)(out + idx + 4) = o1; }
;                     if constexpr (WRITE_XB) {
;                         part += (o0[0] * o0[0] + o0[1] * o0[1]) + (o0[2] * o0[2] + o0[3] * o0[3]) + (o1[0] * o1[0] + o1[1] * o1[1]) + (o1[2] * o1[2] + o1[3] * o1[3]);
;                         u32x4 w; w.x = cvt_pk_bf16(o0[0], o0[1]); w.y = cvt_pk_bf16(o0[2], o0[3]); w.z = cvt_pk_bf16(o1[0], o1[1]); w.w = cvt_pk_bf16(o1[2], o1[3]);
;                         *(u32x4*)(xb + idx) = w; } }
;                 if constexpr (WRITE_XB) { part += __shfl_xor(part, 16); part += __shfl_xor(part, 32);
;                     if (fq == 0) atomicAdd(ss + row, part); } }
;     }
.LBB0_689:
	s_or_b64 exec, exec, s[42:43]
	v_or_b32_e32 v112, 16, v146
	s_waitcnt lgkmcnt(0)
	v_ashrrev_i32_e32 v113, 31, v112
	v_lshlrev_b64 v[116:117], 11, v[112:113]
	v_lshl_add_u64 v[116:117], v[116:117], 0, v[144:145]
	v_lshlrev_b64 v[122:123], 1, v[116:117]
	v_lshl_add_u64 v[116:117], s[14:15], 0, v[122:123]
	s_waitcnt vmcnt(13)
	v_mov_b32_e32 v116, v180
	v_mov_b32_e32 v117, v181
	v_mov_b32_e32 v118, v182
	v_mov_b32_e32 v119, v183
	v_lshl_add_u64 v[124:125], s[16:17], 0, v[122:123]
	v_or_b32_e32 v122, 0x100, v122
	v_lshl_add_u64 v[126:127], s[14:15], 0, v[122:123]
	v_lshlrev_b32_e32 v156, 16, v116
	v_and_b32_e32 v157, 0xffff0000, v116
	v_lshlrev_b32_e32 v116, 16, v117
	v_and_b32_e32 v117, 0xffff0000, v117
	v_lshlrev_b32_e32 v158, 16, v118
	v_and_b32_e32 v159, 0xffff0000, v118
	v_lshlrev_b32_e32 v118, 16, v119
	v_and_b32_e32 v119, 0xffff0000, v119
	v_pk_add_f32 v[116:117], v[110:111], v[116:117]
	v_pk_add_f32 v[156:157], v[108:109], v[156:157]
	v_pk_add_f32 v[118:119], v[106:107], v[118:119]
	v_pk_add_f32 v[158:159], v[104:105], v[158:159]
	v_cvt_pk_bf16_f32 v104, v156, v157
	v_cvt_pk_bf16_f32 v105, v116, v117
	v_mul_f32_e32 v115, v157, v157
	v_cvt_pk_bf16_f32 v106, v158, v159
	v_cvt_pk_bf16_f32 v107, v118, v119
	s_waitcnt vmcnt(12)
	v_mov_b32_e32 v108, v184
	v_mov_b32_e32 v109, v185
	v_mov_b32_e32 v110, v186
	v_mov_b32_e32 v111, v187
	v_mul_f32_e32 v117, v117, v117
	v_mul_f32_e32 v121, v159, v159
	v_fmac_f32_e32 v115, v156, v156
	v_fmac_f32_e32 v117, v116, v116
	v_mul_f32_e32 v119, v119, v119
	v_fmac_f32_e32 v121, v158, v158
	v_add_f32_e32 v115, v115, v117
	v_fmac_f32_e32 v119, v118, v118
	v_add_f32_e32 v115, v121, v115
	v_add_f32_e32 v115, v119, v115
	global_store_dwordx4 v[124:125], v[104:107], off
	v_lshlrev_b32_e32 v116, 16, v108
	v_and_b32_e32 v117, 0xffff0000, v108
	v_lshlrev_b32_e32 v108, 16, v109
	v_and_b32_e32 v109, 0xffff0000, v109
	v_lshlrev_b32_e32 v118, 16, v110
	v_and_b32_e32 v119, 0xffff0000, v110
	v_lshlrev_b32_e32 v110, 16, v111
	v_and_b32_e32 v111, 0xffff0000, v111
	v_pk_add_f32 v[102:103], v[102:103], v[108:109]
	v_pk_add_f32 v[100:101], v[100:101], v[116:117]
	v_pk_add_f32 v[108:109], v[98:99], v[110:111]
	v_pk_add_f32 v[110:111], v[96:97], v[118:119]
	v_mul_f32_e32 v96, v101, v101
	v_mul_f32_e32 v97, v103, v103
	v_mul_f32_e32 v98, v111, v111
	v_fmac_f32_e32 v96, v100, v100
	v_fmac_f32_e32 v97, v102, v102
	v_mul_f32_e32 v99, v109, v109
	v_fmac_f32_e32 v98, v110, v110
	v_add_f32_e32 v96, v96, v97
	v_add_f32_e32 v96, v98, v96
	v_fmac_f32_e32 v99, v108, v108
	v_add_f32_e32 v96, v99, v96
	v_add_f32_e32 v96, v115, v96
	ds_bpermute_b32 v97, v120, v96
	v_cvt_pk_bf16_f32 v98, v100, v101
	v_cvt_pk_bf16_f32 v99, v102, v103
	v_lshl_add_u64 v[102:103], s[16:17], 0, v[122:123]
	v_cvt_pk_bf16_f32 v100, v110, v111
	s_waitcnt lgkmcnt(0)
	v_add_f32_e32 v96, v96, v97
	ds_bpermute_b32 v97, v114, v96
	v_cvt_pk_bf16_f32 v101, v108, v109
	global_store_dwordx4 v[102:103], v[98:101], off
	s_and_saveexec_b64 s[42:43], s[2:3]
	s_cbranch_execz .LBB0_691
	v_lshl_add_u64 v[98:99], v[112:113], 2, s[18:19]
	s_waitcnt lgkmcnt(0)
	v_add_f32_e32 v96, v96, v97
	global_atomic_add_f32 v[98:99], v96, off
.LBB0_691:
	s_or_b64 exec, exec, s[42:43]
	v_or_b32_e32 v96, 32, v146
	s_waitcnt lgkmcnt(0)
	v_ashrrev_i32_e32 v97, 31, v96
	v_lshlrev_b64 v[98:99], 11, v[96:97]
	v_lshl_add_u64 v[98:99], v[98:99], 0, v[144:145]
	v_lshlrev_b64 v[102:103], 1, v[98:99]
	v_lshl_add_u64 v[98:99], s[14:15], 0, v[102:103]
	s_waitcnt vmcnt(11)
	v_mov_b32_e32 v98, v188
	v_mov_b32_e32 v99, v189
	v_mov_b32_e32 v100, v190
	v_mov_b32_e32 v101, v191
	v_lshl_add_u64 v[104:105], s[16:17], 0, v[102:103]
	v_or_b32_e32 v102, 0x100, v102
	v_lshl_add_u64 v[106:107], s[14:15], 0, v[102:103]
	v_lshlrev_b32_e32 v108, 16, v98
	v_and_b32_e32 v109, 0xffff0000, v98
	v_lshlrev_b32_e32 v98, 16, v99
	v_and_b32_e32 v99, 0xffff0000, v99
	v_lshlrev_b32_e32 v110, 16, v100
	v_and_b32_e32 v111, 0xffff0000, v100
	v_lshlrev_b32_e32 v100, 16, v101
	v_and_b32_e32 v101, 0xffff0000, v101
	v_pk_add_f32 v[98:99], v[94:95], v[98:99]
	v_pk_add_f32 v[108:109], v[92:93], v[108:109]
	v_pk_add_f32 v[100:101], v[90:91], v[100:101]
	v_pk_add_f32 v[110:111], v[88:89], v[110:111]
	v_cvt_pk_bf16_f32 v88, v108, v109
	v_cvt_pk_bf16_f32 v89, v98, v99
	v_mul_f32_e32 v99, v99, v99
	v_cvt_pk_bf16_f32 v90, v110, v111
	v_cvt_pk_bf16_f32 v91, v100, v101
	s_waitcnt vmcnt(10)
	v_mov_b32_e32 v92, v192
	v_mov_b32_e32 v93, v193
	v_mov_b32_e32 v94, v194
	v_mov_b32_e32 v95, v195
	v_mul_f32_e32 v106, v109, v109
	v_mul_f32_e32 v107, v111, v111
	v_fmac_f32_e32 v106, v108, v108
	v_fmac_f32_e32 v99, v98, v98
	v_mul_f32_e32 v101, v101, v101
	v_fmac_f32_e32 v107, v110, v110
	v_add_f32_e32 v98, v106, v99
	v_fmac_f32_e32 v101, v100, v100
	v_add_f32_e32 v98, v107, v98
	v_add_f32_e32 v106, v101, v98
	global_store_dwordx4 v[104:105], v[88:91], off
	v_lshlrev_b32_e32 v98, 16, v92
	v_and_b32_e32 v99, 0xffff0000, v92
	v_lshlrev_b32_e32 v92, 16, v93
	v_and_b32_e32 v93, 0xffff0000, v93
	v_lshlrev_b32_e32 v100, 16, v94
	v_and_b32_e32 v101, 0xffff0000, v94
	v_lshlrev_b32_e32 v94, 16, v95
	v_and_b32_e32 v95, 0xffff0000, v95
	v_pk_add_f32 v[86:87], v[86:87], v[92:93]
	v_pk_add_f32 v[84:85], v[84:85], v[98:99]
	v_pk_add_f32 v[92:93], v[82:83], v[94:95]
	v_pk_add_f32 v[94:95], v[80:81], v[100:101]
	v_mul_f32_e32 v80, v85, v85
	v_mul_f32_e32 v81, v87, v87
	v_mul_f32_e32 v82, v95, v95
	v_fmac_f32_e32 v80, v84, v84
	v_fmac_f32_e32 v81, v86, v86
	v_mul_f32_e32 v83, v93, v93
	v_fmac_f32_e32 v82, v94, v94
	v_add_f32_e32 v80, v80, v81
	v_add_f32_e32 v80, v82, v80
	v_fmac_f32_e32 v83, v92, v92
	v_add_f32_e32 v80, v83, v80
	v_add_f32_e32 v80, v106, v80
	ds_bpermute_b32 v81, v120, v80
	v_cvt_pk_bf16_f32 v82, v84, v85
	v_cvt_pk_bf16_f32 v83, v86, v87
	v_lshl_add_u64 v[86:87], s[16:17], 0, v[102:103]
	v_cvt_pk_bf16_f32 v84, v94, v95
	s_waitcnt lgkmcnt(0)
	v_add_f32_e32 v80, v80, v81
	ds_bpermute_b32 v81, v114, v80
	v_cvt_pk_bf16_f32 v85, v92, v93
	global_store_dwordx4 v[86:87], v[82:85], off
	s_and_saveexec_b64 s[42:43], s[2:3]
	s_cbranch_execz .LBB0_693
	v_lshl_add_u64 v[82:83], v[96:97], 2, s[18:19]
	s_waitcnt lgkmcnt(0)
	v_add_f32_e32 v80, v80, v81
	global_atomic_add_f32 v[82:83], v80, off
; __device__ __forceinline__ unsigned cvt_pk_bf16(float lo, float hi) { unsigned r; asm volatile("v_cvt_pk_bf16_f32 %0, %1, %2" : "=v"(r) : "v"(lo), "v"(hi)); return r; }
;     __device__ __forceinline__ void operator()(const f32x4 (&acc)[2][2][4][2], const Unit& u, int wr, int wc, int fr, int fq) const {
;         const int row0 = u.pm * BM + wr * 64 + fr; const int col0 = u.pn * BM + wc * 32 + 8 * fq;
; #pragma unroll
;         for (int ai = 0; ai < 2; ++ai)
; #pragma unroll
;             for (int m = 0; m < 4; ++m) { const int row = row0 + ai * HALF + m * 16; const size_t off = (size_t)row * ldc + col0; float part = 0.f;
; #pragma unroll
;                 for (int bj = 0; bj < 2; ++bj) { const size_t idx = off + bj * HALF;
;                     f32x4 b0, b1;
;                     if constexpr (BASE_BF16) { const u32x4 r = *(const u32x4*)(baseb + idx);
;                         b0 = (f32x4){__builtin_bit_cast(float, r.x << 16), __builtin_bit_cast(float, r.x & 0xffff0000u), __builtin_bit_cast(float, r.y << 16), __builtin_bit_cast(float, r.y & 0xffff0000u)};
;                         b1 = (f32x4){__builtin_bit_cast(float, r.z << 16), __builtin_bit_cast(float, r.z & 0xffff0000u), __builtin_bit_cast(float, r.w << 16), __builtin_bit_cast(float, r.w & 0xffff0000u)}; }
;                     else { b0 = *(const f32x4*)(base + idx); b1 = *(const f32x4*)(base + idx + 4); }
;                     const f32x4 o0 = b0 + acc[ai][bj][m][0] * alpha, o1 = b1 + acc[ai][bj][m][1] * alpha;
;                     if constexpr (WRITE_F32) { *(f32x4*)(out + idx) = o0; *(f32x4*)(out + idx + 4) = o1; }
;                     if constexpr (WRITE_XB) {
;                         part += (o0[0] * o0[0] + o0[1] * o0[1]) + (o0[2] * o0[2] + o0[3] * o0[3]) + (o1[0] * o1[0] + o1[1] * o1[1]) + (o1[2] * o1[2] + o1[3] * o1[3]);
;                         u32x4 w; w.x = cvt_pk_bf16(o0[0], o0[1]); w.y = cvt_pk_bf16(o0[2], o0[3]); w.z = cvt_pk_bf16(o1[0], o1[1]); w.w = cvt_pk_bf16(o1[2], o1[3]);
;                         *(u32x4*)(xb + idx) = w; } }
;                 if constexpr (WRITE_XB) { part += __shfl_xor(part, 16); part += __shfl_xor(part, 32);
;                     if (fq == 0) atomicAdd(ss + row, part); } }
;     }
.LBB0_693:
	s_or_b64 exec, exec, s[42:43]
	v_or_b32_e32 v80, 48, v146
	s_waitcnt lgkmcnt(0)
	v_ashrrev_i32_e32 v81, 31, v80
	v_lshlrev_b64 v[82:83], 11, v[80:81]
	v_lshl_add_u64 v[82:83], v[82:83], 0, v[144:145]
	v_lshlrev_b64 v[86:87], 1, v[82:83]
	v_lshl_add_u64 v[82:83], s[14:15], 0, v[86:87]
	s_waitcnt vmcnt(9)
	v_mov_b32_e32 v82, v196
	v_mov_b32_e32 v83, v197
	v_mov_b32_e32 v84, v198
	v_mov_b32_e32 v85, v199
	v_lshl_add_u64 v[88:89], s[16:17], 0, v[86:87]
	v_or_b32_e32 v86, 0x100, v86
	v_lshl_add_u64 v[90:91], s[14:15], 0, v[86:87]
	v_lshlrev_b32_e32 v92, 16, v82
	v_and_b32_e32 v93, 0xffff0000, v82
	v_lshlrev_b32_e32 v82, 16, v83
	v_and_b32_e32 v83, 0xffff0000, v83
	v_lshlrev_b32_e32 v94, 16, v84
	v_and_b32_e32 v95, 0xffff0000, v84
	v_lshlrev_b32_e32 v84, 16, v85
	v_and_b32_e32 v85, 0xffff0000, v85
	v_pk_add_f32 v[82:83], v[78:79], v[82:83]
	v_pk_add_f32 v[92:93], v[76:77], v[92:93]
	v_pk_add_f32 v[84:85], v[74:75], v[84:85]
	v_pk_add_f32 v[94:95], v[72:73], v[94:95]
	v_cvt_pk_bf16_f32 v72, v92, v93
	v_cvt_pk_bf16_f32 v73, v82, v83
	v_mul_f32_e32 v83, v83, v83
	v_cvt_pk_bf16_f32 v74, v94, v95
	v_cvt_pk_bf16_f32 v75, v84, v85
	s_waitcnt vmcnt(8)
	v_mov_b32_e32 v76, v200
	v_mov_b32_e32 v77, v201
	v_mov_b32_e32 v78, v202
	v_mov_b32_e32 v79, v203
	v_mul_f32_e32 v90, v93, v93
	v_mul_f32_e32 v91, v95, v95
	v_fmac_f32_e32 v90, v92, v92
	v_fmac_f32_e32 v83, v82, v82
	v_mul_f32_e32 v85, v85, v85
	v_fmac_f32_e32 v91, v94, v94
	v_add_f32_e32 v82, v90, v83
	v_fmac_f32_e32 v85, v84, v84
	v_add_f32_e32 v82, v91, v82
	v_add_f32_e32 v90, v85, v82
	global_store_dwordx4 v[88:89], v[72:75], off
	v_lshlrev_b32_e32 v82, 16, v76
	v_and_b32_e32 v83, 0xffff0000, v76
	v_lshlrev_b32_e32 v76, 16, v77
	v_and_b32_e32 v77, 0xffff0000, v77
	v_lshlrev_b32_e32 v84, 16, v78
	v_and_b32_e32 v85, 0xffff0000, v78
	v_lshlrev_b32_e32 v78, 16, v79
	v_and_b32_e32 v79, 0xffff0000, v79
	v_pk_add_f32 v[70:71], v[70:71], v[76:77]
	v_pk_add_f32 v[68:69], v[68:69], v[82:83]
	v_pk_add_f32 v[76:77], v[66:67], v[78:79]
	v_pk_add_f32 v[78:79], v[64:65], v[84:85]
	v_mul_f32_e32 v64, v69, v69
	v_mul_f32_e32 v65, v71, v71
	v_mul_f32_e32 v66, v79, v79
	v_fmac_f32_e32 v64, v68, v68
	v_fmac_f32_e32 v65, v70, v70
	v_mul_f32_e32 v67, v77, v77
	v_fmac_f32_e32 v66, v78, v78
	v_add_f32_e32 v64, v64, v65
	v_add_f32_e32 v64, v66, v64
	v_fmac_f32_e32 v67, v76, v76
	v_add_f32_e32 v64, v67, v64
	v_add_f32_e32 v64, v90, v64
	ds_bpermute_b32 v65, v120, v64
	v_cvt_pk_bf16_f32 v66, v68, v69
	v_cvt_pk_bf16_f32 v67, v70, v71
	v_lshl_add_u64 v[70:71], s[16:17], 0, v[86:87]
	v_cvt_pk_bf16_f32 v68, v78, v79
	s_waitcnt lgkmcnt(0)
	v_add_f32_e32 v64, v64, v65
	ds_bpermute_b32 v65, v114, v64
	v_cvt_pk_bf16_f32 v69, v76, v77
	global_store_dwordx4 v[70:71], v[66:69], off
	s_and_saveexec_b64 s[42:43], s[2:3]
	s_cbranch_execz .LBB0_695
	v_lshl_add_u64 v[66:67], v[80:81], 2, s[18:19]
	s_waitcnt lgkmcnt(0)
	v_add_f32_e32 v64, v64, v65
	global_atomic_add_f32 v[66:67], v64, off
.LBB0_695:
	s_or_b64 exec, exec, s[42:43]
	v_add_u32_e32 v64, 0x80, v146
	s_waitcnt lgkmcnt(0)
	v_ashrrev_i32_e32 v65, 31, v64
	v_lshlrev_b64 v[66:67], 11, v[64:65]
	v_lshl_add_u64 v[66:67], v[66:67], 0, v[144:145]
	v_lshlrev_b64 v[70:71], 1, v[66:67]
	v_lshl_add_u64 v[66:67], s[14:15], 0, v[70:71]
	s_waitcnt vmcnt(7)
	v_mov_b32_e32 v66, v204
	v_mov_b32_e32 v67, v205
	v_mov_b32_e32 v68, v206
	v_mov_b32_e32 v69, v207
	v_lshl_add_u64 v[72:73], s[16:17], 0, v[70:71]
	v_or_b32_e32 v70, 0x100, v70
	v_lshl_add_u64 v[74:75], s[14:15], 0, v[70:71]
	v_lshlrev_b32_e32 v76, 16, v66
	v_and_b32_e32 v77, 0xffff0000, v66
	v_lshlrev_b32_e32 v66, 16, v67
	v_and_b32_e32 v67, 0xffff0000, v67
	v_lshlrev_b32_e32 v78, 16, v68
	v_and_b32_e32 v79, 0xffff0000, v68
	v_lshlrev_b32_e32 v68, 16, v69
	v_and_b32_e32 v69, 0xffff0000, v69
	v_pk_add_f32 v[66:67], v[62:63], v[66:67]
	v_pk_add_f32 v[76:77], v[60:61], v[76:77]
	v_pk_add_f32 v[68:69], v[58:59], v[68:69]
	v_pk_add_f32 v[78:79], v[56:57], v[78:79]
	v_cvt_pk_bf16_f32 v56, v76, v77
	v_cvt_pk_bf16_f32 v57, v66, v67
	v_mul_f32_e32 v67, v67, v67
	v_cvt_pk_bf16_f32 v58, v78, v79
	v_cvt_pk_bf16_f32 v59, v68, v69
	s_waitcnt vmcnt(6)
	v_mov_b32_e32 v60, v208
	v_mov_b32_e32 v61, v209
	v_mov_b32_e32 v62, v210
	v_mov_b32_e32 v63, v211
	v_mul_f32_e32 v74, v77, v77
	v_mul_f32_e32 v75, v79, v79
	v_fmac_f32_e32 v74, v76, v76
	v_fmac_f32_e32 v67, v66, v66
	v_mul_f32_e32 v69, v69, v69
	v_fmac_f32_e32 v75, v78, v78
	v_add_f32_e32 v66, v74, v67
	v_fmac_f32_e32 v69, v68, v68
	v_add_f32_e32 v66, v75, v66
	v_add_f32_e32 v74, v69, v66
	global_store_dwordx4 v[72:73], v[56:59], off
	v_lshlrev_b32_e32 v66, 16, v60
	v_and_b32_e32 v67, 0xffff0000, v60
	v_lshlrev_b32_e32 v60, 16, v61
	v_and_b32_e32 v61, 0xffff0000, v61
	v_lshlrev_b32_e32 v68, 16, v62
	v_and_b32_e32 v69, 0xffff0000, v62
	v_lshlrev_b32_e32 v62, 16, v63
	v_and_b32_e32 v63, 0xffff0000, v63
	v_pk_add_f32 v[54:55], v[54:55], v[60:61]
	v_pk_add_f32 v[52:53], v[52:53], v[66:67]
	v_pk_add_f32 v[60:61], v[50:51], v[62:63]
	v_pk_add_f32 v[62:63], v[48:49], v[68:69]
	v_mul_f32_e32 v48, v53, v53
	v_mul_f32_e32 v49, v55, v55
	v_mul_f32_e32 v50, v63, v63
	v_fmac_f32_e32 v48, v52, v52
	v_fmac_f32_e32 v49, v54, v54
	v_mul_f32_e32 v51, v61, v61
	v_fmac_f32_e32 v50, v62, v62
	v_add_f32_e32 v48, v48, v49
	v_add_f32_e32 v48, v50, v48
	v_fmac_f32_e32 v51, v60, v60
	v_add_f32_e32 v48, v51, v48
	v_add_f32_e32 v48, v74, v48
	ds_bpermute_b32 v49, v120, v48
	v_cvt_pk_bf16_f32 v50, v52, v53
	v_cvt_pk_bf16_f32 v51, v54, v55
	v_lshl_add_u64 v[54:55], s[16:17], 0, v[70:71]
	v_cvt_pk_bf16_f32 v52, v62, v63
	s_waitcnt lgkmcnt(0)
	v_add_f32_e32 v48, v48, v49
	ds_bpermute_b32 v49, v114, v48
	v_cvt_pk_bf16_f32 v53, v60, v61
	global_store_dwordx4 v[54:55], v[50:53], off
	s_and_saveexec_b64 s[42:43], s[2:3]
	s_cbranch_execz .LBB0_697
	v_lshl_add_u64 v[50:51], v[64:65], 2, s[18:19]
	s_waitcnt lgkmcnt(0)
	v_add_f32_e32 v48, v48, v49
	global_atomic_add_f32 v[50:51], v48, off
; __device__ __forceinline__ unsigned cvt_pk_bf16(float lo, float hi) { unsigned r; asm volatile("v_cvt_pk_bf16_f32 %0, %1, %2" : "=v"(r) : "v"(lo), "v"(hi)); return r; }
;     __device__ __forceinline__ void operator()(const f32x4 (&acc)[2][2][4][2], const Unit& u, int wr, int wc, int fr, int fq) const {
;         const int row0 = u.pm * BM + wr * 64 + fr; const int col0 = u.pn * BM + wc * 32 + 8 * fq;
; #pragma unroll
;         for (int ai = 0; ai < 2; ++ai)
; #pragma unroll
;             for (int m = 0; m < 4; ++m) { const int row = row0 + ai * HALF + m * 16; const size_t off = (size_t)row * ldc + col0; float part = 0.f;
; #pragma unroll
;                 for (int bj = 0; bj < 2; ++bj) { const size_t idx = off + bj * HALF;
;                     f32x4 b0, b1;
;                     if constexpr (BASE_BF16) { const u32x4 r = *(const u32x4*)(baseb + idx);
;                         b0 = (f32x4){__builtin_bit_cast(float, r.x << 16), __builtin_bit_cast(float, r.x & 0xffff0000u), __builtin_bit_cast(float, r.y << 16), __builtin_bit_cast(float, r.y & 0xffff0000u)};
;                         b1 = (f32x4){__builtin_bit_cast(float, r.z << 16), __builtin_bit_cast(float, r.z & 0xffff0000u), __builtin_bit_cast(float, r.w << 16), __builtin_bit_cast(float, r.w & 0xffff0000u)}; }
;                     else { b0 = *(const f32x4*)(base + idx); b1 = *(const f32x4*)(base + idx + 4); }
;                     const f32x4 o0 = b0 + acc[ai][bj][m][0] * alpha, o1 = b1 + acc[ai][bj][m][1] * alpha;
;                     if constexpr (WRITE_F32) { *(f32x4*)(out + idx) = o0; *(f32x4*)(out + idx + 4) = o1; }
;                     if constexpr (WRITE_XB) {
;                         part += (o0[0] * o0[0] + o0[1] * o0[1]) + (o0[2] * o0[2] + o0[3] * o0[3]) + (o1[0] * o1[0] + o1[1] * o1[1]) + (o1[2] * o1[2] + o1[3] * o1[3]);
;                         u32x4 w; w.x = cvt_pk_bf16(o0[0], o0[1]); w.y = cvt_pk_bf16(o0[2], o0[3]); w.z = cvt_pk_bf16(o1[0], o1[1]); w.w = cvt_pk_bf16(o1[2], o1[3]);
;                         *(u32x4*)(xb + idx) = w; } }
;                 if constexpr (WRITE_XB) { part += __shfl_xor(part, 16); part += __shfl_xor(part, 32);
;                     if (fq == 0) atomicAdd(ss + row, part); } }
;     }
.LBB0_697:
	s_or_b64 exec, exec, s[42:43]
	v_add_u32_e32 v48, 0x90, v146
	s_waitcnt lgkmcnt(0)
	v_ashrrev_i32_e32 v49, 31, v48
	v_lshlrev_b64 v[50:51], 11, v[48:49]
	v_lshl_add_u64 v[50:51], v[50:51], 0, v[144:145]
	v_lshlrev_b64 v[54:55], 1, v[50:51]
	v_lshl_add_u64 v[50:51], s[14:15], 0, v[54:55]
	s_waitcnt vmcnt(5)
	v_mov_b32_e32 v50, v212
	v_mov_b32_e32 v51, v213
	v_mov_b32_e32 v52, v214
	v_mov_b32_e32 v53, v215
	v_lshl_add_u64 v[56:57], s[16:17], 0, v[54:55]
	v_or_b32_e32 v54, 0x100, v54
	v_lshl_add_u64 v[58:59], s[14:15], 0, v[54:55]
	v_lshlrev_b32_e32 v60, 16, v50
	v_and_b32_e32 v61, 0xffff0000, v50
	v_lshlrev_b32_e32 v50, 16, v51
	v_and_b32_e32 v51, 0xffff0000, v51
	v_lshlrev_b32_e32 v62, 16, v52
	v_and_b32_e32 v63, 0xffff0000, v52
	v_lshlrev_b32_e32 v52, 16, v53
	v_and_b32_e32 v53, 0xffff0000, v53
	v_pk_add_f32 v[50:51], v[46:47], v[50:51]
	v_pk_add_f32 v[60:61], v[44:45], v[60:61]
	v_pk_add_f32 v[52:53], v[42:43], v[52:53]
	v_pk_add_f32 v[62:63], v[40:41], v[62:63]
	v_cvt_pk_bf16_f32 v40, v60, v61
	v_cvt_pk_bf16_f32 v41, v50, v51
	v_mul_f32_e32 v51, v51, v51
	v_cvt_pk_bf16_f32 v42, v62, v63
	v_cvt_pk_bf16_f32 v43, v52, v53
	s_waitcnt vmcnt(4)
	v_mov_b32_e32 v44, v220
	v_mov_b32_e32 v45, v221
	v_mov_b32_e32 v46, v222
	v_mov_b32_e32 v47, v223
	v_mul_f32_e32 v58, v61, v61
	v_mul_f32_e32 v59, v63, v63
	v_fmac_f32_e32 v58, v60, v60
	v_fmac_f32_e32 v51, v50, v50
	v_mul_f32_e32 v53, v53, v53
	v_fmac_f32_e32 v59, v62, v62
	v_add_f32_e32 v50, v58, v51
	v_fmac_f32_e32 v53, v52, v52
	v_add_f32_e32 v50, v59, v50
	v_add_f32_e32 v58, v53, v50
	global_store_dwordx4 v[56:57], v[40:43], off
	v_lshlrev_b32_e32 v50, 16, v44
	v_and_b32_e32 v51, 0xffff0000, v44
	v_lshlrev_b32_e32 v44, 16, v45
	v_and_b32_e32 v45, 0xffff0000, v45
	v_lshlrev_b32_e32 v52, 16, v46
	v_and_b32_e32 v53, 0xffff0000, v46
	v_lshlrev_b32_e32 v46, 16, v47
	v_and_b32_e32 v47, 0xffff0000, v47
	v_pk_add_f32 v[38:39], v[38:39], v[44:45]
	v_pk_add_f32 v[36:37], v[36:37], v[50:51]
	v_pk_add_f32 v[44:45], v[34:35], v[46:47]
	v_pk_add_f32 v[46:47], v[32:33], v[52:53]
	v_mul_f32_e32 v32, v37, v37
	v_mul_f32_e32 v33, v39, v39
	v_mul_f32_e32 v34, v47, v47
	v_fmac_f32_e32 v32, v36, v36
	v_fmac_f32_e32 v33, v38, v38
	v_mul_f32_e32 v35, v45, v45
	v_fmac_f32_e32 v34, v46, v46
	v_add_f32_e32 v32, v32, v33
	v_add_f32_e32 v32, v34, v32
	v_fmac_f32_e32 v35, v44, v44
	v_add_f32_e32 v32, v35, v32
	v_add_f32_e32 v32, v58, v32
	ds_bpermute_b32 v33, v120, v32
	v_cvt_pk_bf16_f32 v34, v36, v37
	v_cvt_pk_bf16_f32 v35, v38, v39
	v_lshl_add_u64 v[38:39], s[16:17], 0, v[54:55]
	v_cvt_pk_bf16_f32 v36, v46, v47
	s_waitcnt lgkmcnt(0)
	v_add_f32_e32 v32, v32, v33
	ds_bpermute_b32 v33, v114, v32
	v_cvt_pk_bf16_f32 v37, v44, v45
	global_store_dwordx4 v[38:39], v[34:37], off
	s_and_saveexec_b64 s[42:43], s[2:3]
	s_cbranch_execz .LBB0_699
	v_lshl_add_u64 v[34:35], v[48:49], 2, s[18:19]
	s_waitcnt lgkmcnt(0)
	v_add_f32_e32 v32, v32, v33
	global_atomic_add_f32 v[34:35], v32, off
; __device__ __forceinline__ unsigned cvt_pk_bf16(float lo, float hi) { unsigned r; asm volatile("v_cvt_pk_bf16_f32 %0, %1, %2" : "=v"(r) : "v"(lo), "v"(hi)); return r; }
;     __device__ __forceinline__ void operator()(const f32x4 (&acc)[2][2][4][2], const Unit& u, int wr, int wc, int fr, int fq) const {
;         const int row0 = u.pm * BM + wr * 64 + fr; const int col0 = u.pn * BM + wc * 32 + 8 * fq;
; #pragma unroll
;         for (int ai = 0; ai < 2; ++ai)
; #pragma unroll
;             for (int m = 0; m < 4; ++m) { const int row = row0 + ai * HALF + m * 16; const size_t off = (size_t)row * ldc + col0; float part = 0.f;
; #pragma unroll
;                 for (int bj = 0; bj < 2; ++bj) { const size_t idx = off + bj * HALF;
;                     f32x4 b0, b1;
;                     if constexpr (BASE_BF16) { const u32x4 r = *(const u32x4*)(baseb + idx);
;                         b0 = (f32x4){__builtin_bit_cast(float, r.x << 16), __builtin_bit_cast(float, r.x & 0xffff0000u), __builtin_bit_cast(float, r.y << 16), __builtin_bit_cast(float, r.y & 0xffff0000u)};
;                         b1 = (f32x4){__builtin_bit_cast(float, r.z << 16), __builtin_bit_cast(float, r.z & 0xffff0000u), __builtin_bit_cast(float, r.w << 16), __builtin_bit_cast(float, r.w & 0xffff0000u)}; }
;                     else { b0 = *(const f32x4*)(base + idx); b1 = *(const f32x4*)(base + idx + 4); }
;                     const f32x4 o0 = b0 + acc[ai][bj][m][0] * alpha, o1 = b1 + acc[ai][bj][m][1] * alpha;
;                     if constexpr (WRITE_F32) { *(f32x4*)(out + idx) = o0; *(f32x4*)(out + idx + 4) = o1; }
;                     if constexpr (WRITE_XB) {
;                         part += (o0[0] * o0[0] + o0[1] * o0[1]) + (o0[2] * o0[2] + o0[3] * o0[3]) + (o1[0] * o1[0] + o1[1] * o1[1]) + (o1[2] * o1[2] + o1[3] * o1[3]);
;                         u32x4 w; w.x = cvt_pk_bf16(o0[0], o0[1]); w.y = cvt_pk_bf16(o0[2], o0[3]); w.z = cvt_pk_bf16(o1[0], o1[1]); w.w = cvt_pk_bf16(o1[2], o1[3]);
;                         *(u32x4*)(xb + idx) = w; } }
;                 if constexpr (WRITE_XB) { part += __shfl_xor(part, 16); part += __shfl_xor(part, 32);
;                     if (fq == 0) atomicAdd(ss + row, part); } }
;     }
.LBB0_699:
	s_or_b64 exec, exec, s[42:43]
	v_add_u32_e32 v32, 0xa0, v146
	s_waitcnt lgkmcnt(0)
	v_ashrrev_i32_e32 v33, 31, v32
	v_lshlrev_b64 v[34:35], 11, v[32:33]
	v_lshl_add_u64 v[34:35], v[34:35], 0, v[144:145]
	v_lshlrev_b64 v[38:39], 1, v[34:35]
	v_lshl_add_u64 v[34:35], s[14:15], 0, v[38:39]
	s_waitcnt vmcnt(3)
	v_mov_b32_e32 v34, v224
	v_mov_b32_e32 v35, v225
	v_mov_b32_e32 v36, v226
	v_mov_b32_e32 v37, v227
	v_lshl_add_u64 v[40:41], s[16:17], 0, v[38:39]
	v_or_b32_e32 v38, 0x100, v38
	v_lshl_add_u64 v[42:43], s[14:15], 0, v[38:39]
	v_lshlrev_b32_e32 v44, 16, v34
	v_and_b32_e32 v45, 0xffff0000, v34
	v_lshlrev_b32_e32 v34, 16, v35
	v_and_b32_e32 v35, 0xffff0000, v35
	v_lshlrev_b32_e32 v46, 16, v36
	v_and_b32_e32 v47, 0xffff0000, v36
	v_lshlrev_b32_e32 v36, 16, v37
	v_and_b32_e32 v37, 0xffff0000, v37
	v_pk_add_f32 v[34:35], v[30:31], v[34:35]
	v_pk_add_f32 v[44:45], v[28:29], v[44:45]
	v_pk_add_f32 v[36:37], v[26:27], v[36:37]
	v_pk_add_f32 v[46:47], v[24:25], v[46:47]
	v_cvt_pk_bf16_f32 v24, v44, v45
	v_cvt_pk_bf16_f32 v25, v34, v35
	v_mul_f32_e32 v35, v35, v35
	v_cvt_pk_bf16_f32 v26, v46, v47
	v_cvt_pk_bf16_f32 v27, v36, v37
	s_waitcnt vmcnt(2)
	v_mov_b32_e32 v28, v228
	v_mov_b32_e32 v29, v229
	v_mov_b32_e32 v30, v230
	v_mov_b32_e32 v31, v231
	v_mul_f32_e32 v42, v45, v45
	v_mul_f32_e32 v43, v47, v47
	v_fmac_f32_e32 v42, v44, v44
	v_fmac_f32_e32 v35, v34, v34
	v_mul_f32_e32 v37, v37, v37
	v_fmac_f32_e32 v43, v46, v46
	v_add_f32_e32 v34, v42, v35
	v_fmac_f32_e32 v37, v36, v36
	v_add_f32_e32 v34, v43, v34
	v_add_f32_e32 v42, v37, v34
	global_store_dwordx4 v[40:41], v[24:27], off
	v_lshlrev_b32_e32 v34, 16, v28
	v_and_b32_e32 v35, 0xffff0000, v28
	v_lshlrev_b32_e32 v28, 16, v29
	v_and_b32_e32 v29, 0xffff0000, v29
	v_lshlrev_b32_e32 v36, 16, v30
	v_and_b32_e32 v37, 0xffff0000, v30
	v_lshlrev_b32_e32 v30, 16, v31
	v_and_b32_e32 v31, 0xffff0000, v31
	v_pk_add_f32 v[22:23], v[22:23], v[28:29]
	v_pk_add_f32 v[20:21], v[20:21], v[34:35]
	v_pk_add_f32 v[28:29], v[18:19], v[30:31]
	v_pk_add_f32 v[30:31], v[16:17], v[36:37]
	v_mul_f32_e32 v16, v21, v21
	v_mul_f32_e32 v17, v23, v23
	v_mul_f32_e32 v18, v31, v31
	v_fmac_f32_e32 v16, v20, v20
	v_fmac_f32_e32 v17, v22, v22
	v_mul_f32_e32 v19, v29, v29
	v_fmac_f32_e32 v18, v30, v30
	v_add_f32_e32 v16, v16, v17
	v_add_f32_e32 v16, v18, v16
	v_fmac_f32_e32 v19, v28, v28
	v_add_f32_e32 v16, v19, v16
	v_add_f32_e32 v16, v42, v16
	ds_bpermute_b32 v17, v120, v16
	v_cvt_pk_bf16_f32 v18, v20, v21
	v_cvt_pk_bf16_f32 v19, v22, v23
	v_lshl_add_u64 v[22:23], s[16:17], 0, v[38:39]
	v_cvt_pk_bf16_f32 v20, v30, v31
	s_waitcnt lgkmcnt(0)
	v_add_f32_e32 v16, v16, v17
	ds_bpermute_b32 v17, v114, v16
	v_cvt_pk_bf16_f32 v21, v28, v29
	global_store_dwordx4 v[22:23], v[18:21], off
	s_and_saveexec_b64 s[42:43], s[2:3]
	s_cbranch_execz .LBB0_701
	v_lshl_add_u64 v[18:19], v[32:33], 2, s[18:19]
	s_waitcnt lgkmcnt(0)
	v_add_f32_e32 v16, v16, v17
	global_atomic_add_f32 v[18:19], v16, off
.LBB0_701:
	s_or_b64 exec, exec, s[42:43]
	v_add_u32_e32 v16, 0xb0, v146
	s_waitcnt lgkmcnt(0)
	v_ashrrev_i32_e32 v17, 31, v16
	v_lshlrev_b64 v[18:19], 11, v[16:17]
	v_lshl_add_u64 v[18:19], v[18:19], 0, v[144:145]
	v_lshlrev_b64 v[22:23], 1, v[18:19]
	v_lshl_add_u64 v[18:19], s[14:15], 0, v[22:23]
	s_waitcnt vmcnt(1)
	v_mov_b32_e32 v18, v232
	v_mov_b32_e32 v19, v233
	v_mov_b32_e32 v20, v234
	v_mov_b32_e32 v21, v235
	v_lshl_add_u64 v[24:25], s[16:17], 0, v[22:23]
	v_or_b32_e32 v22, 0x100, v22
	v_lshl_add_u64 v[26:27], s[14:15], 0, v[22:23]
	v_lshlrev_b32_e32 v28, 16, v18
	v_and_b32_e32 v29, 0xffff0000, v18
	v_lshlrev_b32_e32 v18, 16, v19
	v_and_b32_e32 v19, 0xffff0000, v19
	v_lshlrev_b32_e32 v30, 16, v20
	v_and_b32_e32 v31, 0xffff0000, v20
	v_lshlrev_b32_e32 v20, 16, v21
	v_and_b32_e32 v21, 0xffff0000, v21
	v_pk_add_f32 v[18:19], v[14:15], v[18:19]
	v_pk_add_f32 v[28:29], v[12:13], v[28:29]
	v_pk_add_f32 v[20:21], v[10:11], v[20:21]
	v_pk_add_f32 v[30:31], v[8:9], v[30:31]
	v_cvt_pk_bf16_f32 v8, v28, v29
	v_cvt_pk_bf16_f32 v9, v18, v19
	v_mul_f32_e32 v19, v19, v19
	v_cvt_pk_bf16_f32 v10, v30, v31
	v_cvt_pk_bf16_f32 v11, v20, v21
	s_waitcnt vmcnt(0)
	v_mov_b32_e32 v12, v236
	v_mov_b32_e32 v13, v237
	v_mov_b32_e32 v14, v238
	v_mov_b32_e32 v15, v239
	v_mul_f32_e32 v26, v29, v29
	v_mul_f32_e32 v27, v31, v31
	v_fmac_f32_e32 v26, v28, v28
	v_fmac_f32_e32 v19, v18, v18
	v_mul_f32_e32 v21, v21, v21
	v_fmac_f32_e32 v27, v30, v30
	v_add_f32_e32 v18, v26, v19
	v_fmac_f32_e32 v21, v20, v20
	v_add_f32_e32 v18, v27, v18
	v_add_f32_e32 v26, v21, v18
	global_store_dwordx4 v[24:25], v[8:11], off
	v_lshlrev_b32_e32 v18, 16, v12
	v_and_b32_e32 v19, 0xffff0000, v12
	v_lshlrev_b32_e32 v12, 16, v13
	v_and_b32_e32 v13, 0xffff0000, v13
	v_lshlrev_b32_e32 v20, 16, v14
	v_and_b32_e32 v21, 0xffff0000, v14
	v_lshlrev_b32_e32 v14, 16, v15
	v_and_b32_e32 v15, 0xffff0000, v15
	v_pk_add_f32 v[6:7], v[6:7], v[12:13]
	v_pk_add_f32 v[4:5], v[4:5], v[18:19]
	v_pk_add_f32 v[12:13], v[2:3], v[14:15]
	v_pk_add_f32 v[14:15], v[0:1], v[20:21]
	v_mul_f32_e32 v0, v5, v5
	v_mul_f32_e32 v1, v7, v7
	v_mul_f32_e32 v2, v15, v15
	v_fmac_f32_e32 v0, v4, v4
	v_fmac_f32_e32 v1, v6, v6
	v_mul_f32_e32 v3, v13, v13
	v_fmac_f32_e32 v2, v14, v14
	v_add_f32_e32 v0, v0, v1
	v_add_f32_e32 v0, v2, v0
	v_fmac_f32_e32 v3, v12, v12
	v_add_f32_e32 v0, v3, v0
	v_add_f32_e32 v0, v26, v0
	ds_bpermute_b32 v1, v120, v0
	v_cvt_pk_bf16_f32 v2, v4, v5
	v_cvt_pk_bf16_f32 v3, v6, v7
	v_lshl_add_u64 v[6:7], s[16:17], 0, v[22:23]
	v_cvt_pk_bf16_f32 v4, v14, v15
	s_waitcnt lgkmcnt(0)
	v_add_f32_e32 v0, v0, v1
	ds_bpermute_b32 v1, v114, v0
	v_cvt_pk_bf16_f32 v5, v12, v13
	global_store_dwordx4 v[6:7], v[2:5], off
	s_and_saveexec_b64 s[42:43], s[2:3]
	s_cbranch_execz .LBB0_703
	v_lshl_add_u64 v[2:3], v[16:17], 2, s[18:19]
	s_waitcnt lgkmcnt(0)
	v_add_f32_e32 v0, v0, v1
	global_atomic_add_f32 v[2:3], v0, off
